# full-line nt set plus nt on the attention output (MIX) row stores
# speedup vs baseline: 1.0028x; 1.0028x over previous
.LBB0_499:
	v_lshlrev_b32_e32 v2, 3, v87
	v_lshlrev_b32_e32 v2, 1, v2
	v_lshl_add_u64 v[56:57], s[14:15], 0, v[2:3]
	v_lshl_add_u64 v[64:65], v[56:57], 0, s[18:19]
	v_lshl_add_u64 v[10:11], v[64:65], 0, v[10:11]
	global_load_dwordx4 v[56:59], v[10:11], off nt
	v_lshl_add_u64 v[10:11], v[64:65], 0, v[14:15]
	global_load_dwordx4 v[60:63], v[10:11], off nt
	v_pk_mul_f32 v[10:11], v[36:37], v[54:55] op_sel_hi:[1,0]
	v_pk_mul_f32 v[14:15], v[38:39], v[54:55] op_sel_hi:[1,0]
	v_pk_mul_f32 v[20:21], v[20:21], v[54:55] op_sel_hi:[1,0]
	v_pk_mul_f32 v[22:23], v[22:23], v[54:55] op_sel_hi:[1,0]
	v_cvt_pk_bf16_f32 v10, v10, v11
	v_cvt_pk_bf16_f32 v11, v14, v15
	v_cvt_pk_bf16_f32 v14, v20, v21
	v_lshl_add_u64 v[20:21], v[64:65], 0, v[52:53]
	v_cvt_pk_bf16_f32 v15, v22, v23
	global_load_dwordx4 v[20:23], v[20:21], off nt
	v_pk_mul_f32 v[36:37], v[40:41], v[54:55] op_sel_hi:[1,0]
	v_pk_mul_f32 v[38:39], v[42:43], v[54:55] op_sel_hi:[1,0]
	v_add_u32_e32 v19, 0x1000, v86
	v_pk_mul_f32 v[24:25], v[24:25], v[54:55] op_sel_hi:[1,0]
	v_pk_mul_f32 v[26:27], v[26:27], v[54:55] op_sel_hi:[1,0]
	v_pk_mul_f32 v[40:41], v[44:45], v[54:55] op_sel_hi:[1,0]
	v_pk_mul_f32 v[42:43], v[46:47], v[54:55] op_sel_hi:[1,0]
	v_pk_mul_f32 v[28:29], v[28:29], v[54:55] op_sel_hi:[1,0]
	v_pk_mul_f32 v[30:31], v[30:31], v[54:55] op_sel_hi:[1,0]
	v_pk_mul_f32 v[44:45], v[48:49], v[54:55] op_sel_hi:[1,0]
	v_pk_mul_f32 v[46:47], v[50:51], v[54:55] op_sel_hi:[1,0]
	v_pk_mul_f32 v[32:33], v[32:33], v[54:55] op_sel_hi:[1,0]
	v_pk_mul_f32 v[34:35], v[34:35], v[54:55] op_sel_hi:[1,0]
	v_cvt_pk_bf16_f32 v36, v36, v37
	v_cvt_pk_bf16_f32 v37, v38, v39
	v_cvt_pk_bf16_f32 v24, v24, v25
	v_cvt_pk_bf16_f32 v25, v26, v27
	v_cvt_pk_bf16_f32 v26, v40, v41
	v_cvt_pk_bf16_f32 v27, v42, v43
	v_cvt_pk_bf16_f32 v28, v28, v29
	v_cvt_pk_bf16_f32 v29, v30, v31
	v_cvt_pk_bf16_f32 v30, v44, v45
	v_cvt_pk_bf16_f32 v31, v46, v47
	v_cvt_pk_bf16_f32 v32, v32, v33
	v_cvt_pk_bf16_f32 v33, v34, v35
	ds_write2_b64 v19, v[10:11], v[36:37] offset0:64 offset1:66
	ds_write2_b64 v19, v[14:15], v[24:25] offset0:72 offset1:74
	ds_write2_b64 v19, v[26:27], v[30:31] offset0:68 offset1:70
	ds_write2_b64 v19, v[28:29], v[32:33] offset0:76 offset1:78
	v_lshl_add_u64 v[10:11], v[64:65], 0, v[12:13]
	global_load_dwordx4 v[10:13], v[10:11], off nt
	s_waitcnt lgkmcnt(0)
	ds_read_b128 v[24:27], v55 offset:4608
	v_lshl_add_u64 v[14:15], s[24:25], 0, v[2:3]
	v_lshl_add_u64 v[28:29], v[14:15], 0, s[20:21]
	v_lshl_add_u64 v[30:31], v[28:29], 0, v[16:17]
	v_lshl_add_u64 v[4:5], v[28:29], 0, v[4:5]
	s_waitcnt lgkmcnt(0)
	v_lshlrev_b32_e32 v14, 16, v24
	v_and_b32_e32 v15, 0xffff0000, v24
	v_lshlrev_b32_e32 v16, 16, v25
	v_and_b32_e32 v17, 0xffff0000, v25
	v_lshlrev_b32_e32 v24, 16, v26
	v_and_b32_e32 v25, 0xffff0000, v26
	v_lshlrev_b32_e32 v26, 16, v27
	v_and_b32_e32 v27, 0xffff0000, v27
	v_lshl_add_u64 v[8:9], v[28:29], 0, v[8:9]
	s_waitcnt vmcnt(3)
	v_lshlrev_b32_e32 v32, 16, v56
	v_and_b32_e32 v33, 0xffff0000, v56
	v_lshlrev_b32_e32 v34, 16, v57
	v_and_b32_e32 v35, 0xffff0000, v57
	v_lshlrev_b32_e32 v36, 16, v58
	v_and_b32_e32 v37, 0xffff0000, v58
	v_lshlrev_b32_e32 v38, 16, v59
	v_and_b32_e32 v39, 0xffff0000, v59
	v_pk_mul_f32 v[14:15], v[32:33], v[14:15]
	v_pk_mul_f32 v[16:17], v[34:35], v[16:17]
	v_pk_mul_f32 v[24:25], v[36:37], v[24:25]
	v_pk_mul_f32 v[26:27], v[38:39], v[26:27]
	v_cvt_pk_bf16_f32 v14, v14, v15
	v_cvt_pk_bf16_f32 v15, v16, v17
	v_cvt_pk_bf16_f32 v16, v24, v25
	v_cvt_pk_bf16_f32 v17, v26, v27
	global_store_dwordx4 v[30:31], v[14:17], off sc0 sc1 nt
	s_nop 1
	ds_read_b128 v[14:17], v55 offset:5760
	s_waitcnt vmcnt(2)
	v_lshlrev_b32_e32 v24, 16, v61
	v_and_b32_e32 v25, 0xffff0000, v61
	v_lshlrev_b32_e32 v26, 16, v62
	v_and_b32_e32 v27, 0xffff0000, v62
	s_waitcnt lgkmcnt(0)
	v_lshlrev_b32_e32 v30, 16, v14
	v_and_b32_e32 v31, 0xffff0000, v14
	v_lshlrev_b32_e32 v14, 16, v15
	v_and_b32_e32 v15, 0xffff0000, v15
	v_lshlrev_b32_e32 v32, 16, v16
	v_and_b32_e32 v33, 0xffff0000, v16
	v_pk_mul_f32 v[24:25], v[24:25], v[14:15]
	v_lshlrev_b32_e32 v40, 16, v60
	v_cvt_pk_bf16_f32 v15, v24, v25
	v_pk_mul_f32 v[24:25], v[26:27], v[32:33]
	v_and_b32_e32 v41, 0xffff0000, v60
	v_cvt_pk_bf16_f32 v16, v24, v25
	v_lshlrev_b32_e32 v24, 16, v17
	v_and_b32_e32 v25, 0xffff0000, v17
	v_lshlrev_b32_e32 v26, 16, v63
	v_and_b32_e32 v27, 0xffff0000, v63
	v_pk_mul_f32 v[30:31], v[40:41], v[30:31]
	v_pk_mul_f32 v[24:25], v[26:27], v[24:25]
	v_cvt_pk_bf16_f32 v14, v30, v31
	v_cvt_pk_bf16_f32 v17, v24, v25
	global_store_dwordx4 v[4:5], v[14:17], off sc0 sc1 nt
	s_nop 1
	ds_read_b128 v[14:17], v55 offset:6912
	s_waitcnt vmcnt(1)
	v_lshlrev_b32_e32 v24, 16, v20
	v_and_b32_e32 v25, 0xffff0000, v20
	v_lshlrev_b32_e32 v20, 16, v21
	v_and_b32_e32 v21, 0xffff0000, v21
	s_waitcnt lgkmcnt(0)
	v_lshlrev_b32_e32 v4, 16, v14
	v_and_b32_e32 v5, 0xffff0000, v14
	v_pk_mul_f32 v[4:5], v[24:25], v[4:5]
	s_nop 0
	v_cvt_pk_bf16_f32 v14, v4, v5
	v_lshlrev_b32_e32 v4, 16, v15
	v_and_b32_e32 v5, 0xffff0000, v15
	v_pk_mul_f32 v[4:5], v[20:21], v[4:5]
	v_lshlrev_b32_e32 v20, 16, v22
	v_cvt_pk_bf16_f32 v15, v4, v5
	v_lshlrev_b32_e32 v4, 16, v16
	v_and_b32_e32 v5, 0xffff0000, v16
	v_and_b32_e32 v21, 0xffff0000, v22
	v_pk_mul_f32 v[4:5], v[20:21], v[4:5]
	v_lshlrev_b32_e32 v20, 16, v23
	v_cvt_pk_bf16_f32 v16, v4, v5
	v_lshlrev_b32_e32 v4, 16, v17
	v_and_b32_e32 v5, 0xffff0000, v17
	v_and_b32_e32 v21, 0xffff0000, v23
	v_pk_mul_f32 v[4:5], v[20:21], v[4:5]
	s_nop 0
	v_cvt_pk_bf16_f32 v17, v4, v5
	v_lshl_add_u64 v[4:5], v[28:29], 0, v[6:7]
	global_store_dwordx4 v[4:5], v[14:17], off sc0 sc1 nt
	s_nop 1
	ds_read_b128 v[4:7], v55 offset:8064
	s_waitcnt vmcnt(0)
	v_lshlrev_b32_e32 v16, 16, v10
	v_and_b32_e32 v17, 0xffff0000, v10
	v_lshlrev_b32_e32 v10, 16, v11
	v_and_b32_e32 v11, 0xffff0000, v11
	s_waitcnt lgkmcnt(0)
	v_lshlrev_b32_e32 v14, 16, v4
	v_and_b32_e32 v15, 0xffff0000, v4
	v_pk_mul_f32 v[14:15], v[16:17], v[14:15]
	s_nop 0
	v_cvt_pk_bf16_f32 v4, v14, v15
	v_lshlrev_b32_e32 v14, 16, v5
	v_and_b32_e32 v15, 0xffff0000, v5
	v_pk_mul_f32 v[10:11], v[10:11], v[14:15]
	v_lshlrev_b32_e32 v14, 16, v12
	v_cvt_pk_bf16_f32 v5, v10, v11
	v_lshlrev_b32_e32 v10, 16, v6
	v_and_b32_e32 v11, 0xffff0000, v6
	v_and_b32_e32 v15, 0xffff0000, v12
	v_pk_mul_f32 v[10:11], v[14:15], v[10:11]
	v_lshlrev_b32_e32 v12, 16, v13
	v_cvt_pk_bf16_f32 v6, v10, v11
	v_lshlrev_b32_e32 v10, 16, v7
	v_and_b32_e32 v11, 0xffff0000, v7
	v_and_b32_e32 v13, 0xffff0000, v13
	v_pk_mul_f32 v[10:11], v[12:13], v[10:11]
	s_nop 0
	v_cvt_pk_bf16_f32 v7, v10, v11
	global_store_dwordx4 v[8:9], v[4:7], off sc0 sc1 nt
	s_nop 1

.LBB0_576:
	s_mov_b32 s25, s36
	s_waitcnt lgkmcnt(0)
	s_add_u32 s28, s26, s14
	s_addc_u32 s29, s27, s15
	s_lshl_b64 s[14:15], s[24:25], 10
	s_add_u32 s14, s28, s14
	s_addc_u32 s15, s29, s15
	s_lshl_b32 s28, s68, 1
	s_add_u32 s14, s14, s28
	v_ashrrev_i32_e32 v16, 3, v186
	v_and_b32_e32 v87, 7, v186
	s_addc_u32 s15, s15, 0
	v_lshlrev_b32_e32 v2, 4, v87
	v_ashrrev_i32_e32 v17, 31, v16
	v_lshl_add_u64 v[88:89], s[14:15], 0, v[2:3]
	v_lshlrev_b64 v[10:11], 10, v[16:17]
	v_lshl_add_u64 v[6:7], v[88:89], 0, v[10:11]
	global_load_dwordx4 v[6:9], v[6:7], off nt
	v_mov_b32_e32 v5, s63
	v_ashrrev_i32_e32 v12, 2, v186
	v_mad_u32_u24 v5, v188, s67, v5
	v_and_b32_e32 v12, -8, v12
	v_add_u32_e32 v86, v5, v12
	v_pk_mul_f32 v[12:13], v[52:53], v[4:5] op_sel_hi:[1,0]
	v_pk_mul_f32 v[14:15], v[54:55], v[4:5] op_sel_hi:[1,0]
	v_cvt_pk_bf16_f32 v12, v12, v13
	v_cvt_pk_bf16_f32 v13, v14, v15
	v_pk_mul_f32 v[14:15], v[68:69], v[4:5] op_sel_hi:[1,0]
	v_add_u32_e32 v90, 8, v16
	v_cvt_pk_bf16_f32 v52, v14, v15
	v_pk_mul_f32 v[14:15], v[70:71], v[4:5] op_sel_hi:[1,0]
	v_ashrrev_i32_e32 v91, 31, v90
	v_cvt_pk_bf16_f32 v53, v14, v15
	v_pk_mul_f32 v[14:15], v[56:57], v[4:5] op_sel_hi:[1,0]
	v_pk_mul_f32 v[68:69], v[58:59], v[4:5] op_sel_hi:[1,0]
	v_cvt_pk_bf16_f32 v54, v14, v15
	v_lshlrev_b64 v[14:15], 10, v[90:91]
	v_lshl_add_u64 v[56:57], v[88:89], 0, v[14:15]
	global_load_dwordx4 v[56:59], v[56:57], off nt
	v_cvt_pk_bf16_f32 v55, v68, v69
	ds_write2_b64 v86, v[12:13], v[54:55] offset1:2
	v_pk_mul_f32 v[12:13], v[72:73], v[4:5] op_sel_hi:[1,0]
	v_pk_mul_f32 v[54:55], v[74:75], v[4:5] op_sel_hi:[1,0]
	v_cvt_pk_bf16_f32 v12, v12, v13
	v_cvt_pk_bf16_f32 v13, v54, v55
	ds_write2_b64 v86, v[52:53], v[12:13] offset0:8 offset1:10
	v_pk_mul_f32 v[12:13], v[60:61], v[4:5] op_sel_hi:[1,0]
	v_pk_mul_f32 v[52:53], v[62:63], v[4:5] op_sel_hi:[1,0]
	v_cvt_pk_bf16_f32 v12, v12, v13
	v_cvt_pk_bf16_f32 v13, v52, v53
	v_pk_mul_f32 v[52:53], v[76:77], v[4:5] op_sel_hi:[1,0]
	v_pk_mul_f32 v[54:55], v[78:79], v[4:5] op_sel_hi:[1,0]
	v_cvt_pk_bf16_f32 v52, v52, v53
	v_cvt_pk_bf16_f32 v53, v54, v55
	v_pk_mul_f32 v[54:55], v[64:65], v[4:5] op_sel_hi:[1,0]
	v_pk_mul_f32 v[60:61], v[66:67], v[4:5] op_sel_hi:[1,0]
	v_cvt_pk_bf16_f32 v54, v54, v55
	v_cvt_pk_bf16_f32 v55, v60, v61
	ds_write2_b64 v86, v[12:13], v[54:55] offset0:4 offset1:6
	v_pk_mul_f32 v[12:13], v[80:81], v[4:5] op_sel_hi:[1,0]
	v_pk_mul_f32 v[4:5], v[82:83], v[4:5] op_sel_hi:[1,0]
	v_add_u32_e32 v72, 16, v16
	v_cvt_pk_bf16_f32 v12, v12, v13
	v_cvt_pk_bf16_f32 v13, v4, v5
	v_ashrrev_i32_e32 v73, 31, v72
	ds_write2_b64 v86, v[52:53], v[12:13] offset0:12 offset1:14
	v_lshlrev_b64 v[52:53], 10, v[72:73]
	v_lshl_add_u64 v[4:5], v[88:89], 0, v[52:53]
	global_load_dwordx4 v[60:63], v[4:5], off nt
	v_add_u32_e32 v74, 24, v16
	v_ashrrev_i32_e32 v75, 31, v74
	v_lshlrev_b64 v[12:13], 10, v[74:75]
	v_lshl_add_u64 v[4:5], v[88:89], 0, v[12:13]
	global_load_dwordx4 v[64:67], v[4:5], off nt
	s_waitcnt lgkmcnt(0)
	v_add_u32_e32 v4, s63, v2
	v_mul_lo_u32 v5, v16, s67
	v_add_u32_e32 v55, v4, v5
	s_lshl_b64 s[24:25], s[24:25], 11
	ds_read_b128 v[68:71], v55
	s_add_u32 s24, s26, s24
	s_addc_u32 s25, s27, s25
	s_lshl_b32 s26, s30, 1
	s_add_u32 s24, s24, s26
	s_addc_u32 s25, s25, 0
	s_add_u32 s24, s24, s28
	s_waitcnt lgkmcnt(0)
	v_lshlrev_b32_e32 v4, 16, v68
	v_and_b32_e32 v5, 0xffff0000, v68
	v_lshlrev_b32_e32 v68, 16, v69
	v_and_b32_e32 v69, 0xffff0000, v69
	s_addc_u32 s25, s25, 0
	s_add_u32 s24, s24, 0x5400000
	s_addc_u32 s25, s25, 0
	v_lshl_add_u64 v[76:77], s[24:25], 0, v[2:3]
	v_lshlrev_b64 v[16:17], 11, v[16:17]
	s_and_b64 vcc, exec, s[6:7]
	s_waitcnt vmcnt(3)
	v_lshlrev_b32_e32 v78, 16, v6
	v_and_b32_e32 v79, 0xffff0000, v6
	v_lshlrev_b32_e32 v6, 16, v7
	v_and_b32_e32 v7, 0xffff0000, v7
	v_pk_mul_f32 v[4:5], v[78:79], v[4:5]
	v_pk_mul_f32 v[6:7], v[6:7], v[68:69]
	v_cvt_pk_bf16_f32 v4, v4, v5
	v_cvt_pk_bf16_f32 v5, v6, v7
	v_lshlrev_b32_e32 v6, 16, v70
	v_and_b32_e32 v7, 0xffff0000, v70
	v_lshlrev_b32_e32 v68, 16, v8
	v_and_b32_e32 v69, 0xffff0000, v8
	v_pk_mul_f32 v[6:7], v[68:69], v[6:7]
	v_lshlrev_b32_e32 v68, 16, v71
	v_and_b32_e32 v69, 0xffff0000, v71
	v_lshlrev_b32_e32 v8, 16, v9
	v_and_b32_e32 v9, 0xffff0000, v9
	v_pk_mul_f32 v[8:9], v[8:9], v[68:69]
	v_cvt_pk_bf16_f32 v6, v6, v7
	v_cvt_pk_bf16_f32 v7, v8, v9
	v_lshl_add_u64 v[8:9], v[76:77], 0, v[16:17]
	global_store_dwordx4 v[8:9], v[4:7], off sc0 sc1 nt
	s_nop 1
	ds_read_b128 v[4:7], v55 offset:1152
	s_waitcnt vmcnt(2)
	v_lshlrev_b32_e32 v68, 16, v56
	v_and_b32_e32 v69, 0xffff0000, v56
	s_waitcnt lgkmcnt(0)
	v_lshlrev_b32_e32 v8, 16, v4
	v_and_b32_e32 v9, 0xffff0000, v4
	v_pk_mul_f32 v[8:9], v[68:69], v[8:9]
	v_lshlrev_b32_e32 v4, 16, v5
	v_cvt_pk_bf16_f32 v56, v8, v9
	v_and_b32_e32 v5, 0xffff0000, v5
	v_lshlrev_b32_e32 v8, 16, v57
	v_and_b32_e32 v9, 0xffff0000, v57
	v_pk_mul_f32 v[4:5], v[8:9], v[4:5]
	v_lshlrev_b32_e32 v8, 16, v58
	v_cvt_pk_bf16_f32 v57, v4, v5
	v_lshlrev_b32_e32 v4, 16, v6
	v_and_b32_e32 v5, 0xffff0000, v6
	v_and_b32_e32 v9, 0xffff0000, v58
	v_pk_mul_f32 v[4:5], v[8:9], v[4:5]
	v_lshlrev_b32_e32 v6, 16, v59
	v_cvt_pk_bf16_f32 v58, v4, v5
	v_lshlrev_b32_e32 v4, 16, v7
	v_and_b32_e32 v5, 0xffff0000, v7
	v_and_b32_e32 v7, 0xffff0000, v59
	v_pk_mul_f32 v[4:5], v[6:7], v[4:5]
	s_nop 0
	v_cvt_pk_bf16_f32 v59, v4, v5
	v_lshlrev_b64 v[4:5], 11, v[90:91]
	v_lshl_add_u64 v[6:7], v[76:77], 0, v[4:5]
	global_store_dwordx4 v[6:7], v[56:59], off sc0 sc1 nt
	s_nop 1
	ds_read_b128 v[6:9], v55 offset:2304
	s_waitcnt vmcnt(1)
	v_lshlrev_b32_e32 v58, 16, v60
	v_and_b32_e32 v59, 0xffff0000, v60
	s_waitcnt vmcnt(0)
	v_lshlrev_b32_e32 v60, 16, v64
	s_waitcnt lgkmcnt(0)
	v_lshlrev_b32_e32 v56, 16, v6
	v_and_b32_e32 v57, 0xffff0000, v6
	v_pk_mul_f32 v[56:57], v[58:59], v[56:57]
	v_lshlrev_b32_e32 v6, 16, v7
	v_and_b32_e32 v7, 0xffff0000, v7
	v_lshlrev_b32_e32 v58, 16, v61
	v_and_b32_e32 v59, 0xffff0000, v61
	v_pk_mul_f32 v[6:7], v[58:59], v[6:7]
	v_cvt_pk_bf16_f32 v56, v56, v57
	v_cvt_pk_bf16_f32 v57, v6, v7
	v_lshlrev_b32_e32 v6, 16, v8
	v_and_b32_e32 v7, 0xffff0000, v8
	v_lshlrev_b32_e32 v58, 16, v62
	v_and_b32_e32 v59, 0xffff0000, v62
	v_pk_mul_f32 v[6:7], v[58:59], v[6:7]
	v_lshlrev_b32_e32 v8, 16, v63
	v_cvt_pk_bf16_f32 v58, v6, v7
	v_lshlrev_b32_e32 v6, 16, v9
	v_and_b32_e32 v7, 0xffff0000, v9
	v_and_b32_e32 v9, 0xffff0000, v63
	v_pk_mul_f32 v[6:7], v[8:9], v[6:7]
	v_and_b32_e32 v61, 0xffff0000, v64
	v_cvt_pk_bf16_f32 v59, v6, v7
	v_lshlrev_b64 v[6:7], 11, v[72:73]
	v_lshl_add_u64 v[8:9], v[76:77], 0, v[6:7]
	global_store_dwordx4 v[8:9], v[56:59], off sc0 sc1 nt
	s_nop 1
	ds_read_b128 v[56:59], v55 offset:3456
	s_waitcnt lgkmcnt(0)
	v_lshlrev_b32_e32 v8, 16, v56
	v_and_b32_e32 v9, 0xffff0000, v56
	v_pk_mul_f32 v[8:9], v[60:61], v[8:9]
	v_lshlrev_b32_e32 v60, 16, v65
	v_cvt_pk_bf16_f32 v56, v8, v9
	v_lshlrev_b32_e32 v8, 16, v57
	v_and_b32_e32 v9, 0xffff0000, v57
	v_and_b32_e32 v61, 0xffff0000, v65
	v_pk_mul_f32 v[8:9], v[60:61], v[8:9]
	v_lshlrev_b32_e32 v60, 16, v66
	v_cvt_pk_bf16_f32 v57, v8, v9
	v_lshlrev_b32_e32 v8, 16, v58
	v_and_b32_e32 v9, 0xffff0000, v58
	v_and_b32_e32 v61, 0xffff0000, v66
	v_pk_mul_f32 v[8:9], v[60:61], v[8:9]
	v_lshlrev_b32_e32 v60, 16, v67
	v_cvt_pk_bf16_f32 v58, v8, v9
	v_lshlrev_b32_e32 v8, 16, v59
	v_and_b32_e32 v9, 0xffff0000, v59
	v_and_b32_e32 v61, 0xffff0000, v67
	v_pk_mul_f32 v[8:9], v[60:61], v[8:9]
	s_nop 0
	v_cvt_pk_bf16_f32 v59, v8, v9
	v_lshlrev_b64 v[8:9], 11, v[74:75]
	v_lshl_add_u64 v[60:61], v[76:77], 0, v[8:9]
	global_store_dwordx4 v[60:61], v[56:59], off sc0 sc1 nt
	s_nop 1
	s_cbranch_vccnz .LBB0_500
	s_and_b64 vcc, exec, s[8:9]
	s_mov_b64 s[6:7], -1
	s_cbranch_vccnz .LBB0_579
	v_max_f32_e32 v2, v85, v85
	v_max_f32_e32 v54, v19, v19
	v_max_f32_e32 v2, v54, v2
	v_sub_f32_e32 v19, v19, v2
	v_sub_f32_e32 v2, v85, v2
	v_exp_f32_e32 v19, v19
	v_exp_f32_e32 v2, v2
	s_nop 0
	v_fmac_f32_e32 v2, v84, v19
	v_div_scale_f32 v54, s[6:7], v2, v2, v19
	v_rcp_f32_e32 v56, v54
	v_div_scale_f32 v57, vcc, v19, v2, v19
	s_mov_b64 s[6:7], 0
	v_fma_f32 v58, -v54, v56, 1.0
	v_fmac_f32_e32 v56, v58, v56
	v_mul_f32_e32 v58, v57, v56
	v_fma_f32 v59, -v54, v58, v57
	v_fmac_f32_e32 v58, v59, v56
	v_fma_f32 v54, -v54, v58, v57
	v_div_fmas_f32 v54, v54, v56, v58
	v_div_fixup_f32 v54, v54, v2, v19
